# P0: waves 4-7 run RMSNorm first and weight conversion second (waves 0-3 keep conversion first) so the two traffic patterns overlap; plus nt on once-read loads
# speedup vs baseline: 1.0074x; 1.0014x over previous
; #define LAS __attribute__((address_space(3)))
; #define KARG ((const __attribute__((address_space(4))) Args*)__builtin_amdgcn_kernarg_segment_ptr())
; __device__ __forceinline__ unsigned xb_add(unsigned* p, unsigned v) { return __hip_atomic_fetch_add(p, v, __ATOMIC_RELAXED, __HIP_MEMORY_SCOPE_AGENT); }
; __device__ __forceinline__ unsigned xb_xcc_id() { return (unsigned)__builtin_amdgcn_s_getreg((3 << 11) | 20) & 0xFu; }
; __device__ __forceinline__ XcdBarrier xcd_barrier_post(unsigned* bar, volatile LAS unsigned* st) {
;     XcdBarrier b; b.bar = bar; b.x = xb_xcc_id(); b.st = st;
;     if (threadIdx.x == 0) (void)xb_add(&bar[XB_XCNT(b.x)], 1u);
;     return b;
; __global__ void __launch_bounds__(NWAVES * 64, 2) hymba_fwd(Args args) {
;     extern __shared__ __attribute__((aligned(16))) unsigned char lds_raw[];
;     Frame F; F.lds = (LAS unsigned char*)lds_raw; F.tid = threadIdx.x; F.lane = F.tid & 63; F.wave = __builtin_amdgcn_readfirstlane(F.tid >> 6); F.G = KARG->grid; F.bid = blockIdx.x;
;     volatile LAS unsigned* MISC = (volatile LAS unsigned*)(F.lds + MISC_OFF);
;     Ptrs P;
;     for (int u = F.tid; u < (LDS_BYTES - LDSCTL_OFF) / 4; u += NWAVES * 64) ((LAS unsigned*)(F.lds + LDSCTL_OFF))[u] = 0u;
;     __syncthreads();
;     if (N_LAUNCHES == 1) (void)xcd_barrier_post((unsigned*)(P_ctl + CW_BAR), MISC + 8);
_Z9hymba_fwd4Args:
	s_mov_b32 s98, 0
	s_movk_i32 s3, 0x1c0
	v_readfirstlane_b32 s60, v0
	v_cmp_gt_u32_e32 vcc, s3, v0
	s_and_saveexec_b64 s[4:5], vcc
	v_lshl_add_u32 v1, v0, 2, 0
	v_add_u32_e32 v1, 0x23900, v1
	v_mov_b32_e32 v2, 0
	ds_write_b32 v1, v2
	s_or_b64 exec, exec, s[4:5]
	s_load_dword s3, s[0:1], 0xe8
	s_waitcnt lgkmcnt(0)
	s_barrier
	s_load_dwordx2 s[50:51], s[0:1], 0xd8
	s_getreg_b32 s8, hwreg(HW_REG_XCC_ID, 0, 4)
	v_cmp_eq_u32_e64 s[48:49], 0, v0
	s_waitcnt lgkmcnt(0)
	s_add_u32 s4, s50, 0x4000
	s_addc_u32 s5, s51, 0
	v_writelane_b32 v255, s4, 0
	s_nop 1
	v_writelane_b32 v255, s5, 1
	s_and_saveexec_b64 s[4:5], s[48:49]
	s_cbranch_execz .LBB0_5
	s_mov_b64 s[6:7], exec
	v_mbcnt_lo_u32_b32 v1, s6, 0
	v_mbcnt_hi_u32_b32 v1, s7, v1
	v_cmp_eq_u32_e32 vcc, 0, v1
	s_and_b64 s[10:11], exec, vcc
	s_mov_b64 exec, s[10:11]
	s_cbranch_execz .LBB0_5
	s_lshl_b32 s8, s8, 8
	s_bcnt1_i32_b64 s6, s[6:7]
	s_and_b32 s8, s8, 0xf00
	v_mov_b32_e32 v2, s6
	v_readlane_b32 s6, v255, 0
	v_mov_b32_e32 v1, s8
	v_readlane_b32 s7, v255, 1
	s_nop 4
	global_atomic_add v1, v2, s[6:7] offset:1024

; #define LAS __attribute__((address_space(3)))
; template <int WHICH> __device__ __forceinline__ void convert_weights(const Frame& F, int gw, int ngw) {
;     LAS float* scr = (LAS float*)(F.lds + RING_OFF + F.wave * 16384);
;     constexpr int NIT = WHICH == 0 ? I_1 + I_2 : (WHICH == 3 ? 2 * I_3 : I_4);
;     for (int it = gw; it < NIT; it += ngw) {
;         if (WHICH == 0) { if (it < I_1) p0_transpose_item(P_w_in, DM, 9248, P_W1, 0, scr, it, F.lane); else p0_transpose_item(P_w_out, DM, DM, P_W2, 4, scr, it - I_1, F.lane); }
; __device__ __forceinline__ void p0_prologue(const Frame& F, const Ptrs& P) {
;     const int gw = F.bid * NWAVES + F.wave, NGW = F.G * NWAVES;
;     convert_weights<0>(F, gw, NGW);
;     for (int m = gw; m < M; m += NGW) { const float* xr = (m < MP) ? P_x_prompt + (size_t)m * DM : P_x_sample + (size_t)(m - MP) * DM; rms_row_to_bf16(xr, P_mix_nw, P_XN + (size_t)m * DM, F.lane); }
.Lp0_conv_entry:
	s_lshl_b32 s4, s2, 3
	s_add_i32 s8, s94, s4
	s_lshl_b32 s10, s3, 3
	s_cmp_lg_u32 s98, 0
	s_cbranch_scc1 .Lp0_conv_go
	s_cmp_lt_u32 s94, 4
	s_cbranch_scc1 .Lp0_conv_go
	s_mov_b32 s98, 1
	s_branch .LBB0_13
.Lp0_conv_go:
	s_cmpk_gt_i32 s8, 0x683f
	s_cbranch_scc1 .LBB0_13
	s_lshl_b32 s4, s94, 14
	s_add_i32 s9, s4, 0
	v_lshrrev_b32_e32 v1, 5, v189
	v_and_b32_e32 v14, 31, v0
	v_and_b32_e32 v2, 7, v0
	v_lshrrev_b32_e32 v7, 3, v189
	v_mov_b32_e32 v3, 0
	v_lshl_add_u32 v12, v14, 2, s9
	v_mul_u32_u24_e32 v13, 0x84, v1
	v_lshlrev_b32_e32 v6, 3, v2
	v_mul_u32_u24_e32 v4, 0x420, v2
	v_lshlrev_b32_e32 v5, 2, v7
	v_lshlrev_b32_e32 v2, 4, v2
	s_add_u32 s4, s50, 0x19600000
	v_add3_u32 v8, s9, v4, v5
	v_lshl_add_u64 v[4:5], s[50:51], 0, v[2:3]
	s_mov_b64 s[12:13], 0x14c00000
	v_add_u32_e32 v12, v12, v13
	s_addc_u32 s5, s51, 0
	v_or_b32_e32 v9, 8, v7
	v_or_b32_e32 v10, 16, v7
	v_or_b32_e32 v11, 24, v7
	v_lshl_add_u64 v[4:5], v[4:5], 0, s[12:13]
	s_lshl_b32 s9, s8, 5
	s_lshl_b32 s11, s10, 5
	s_mov_b32 s16, 0x8000
	s_mov_b32 s17, 0x10000
	s_mov_b32 s18, 0x18000
	s_mov_b32 s19, 0x20000
	s_mov_b32 s20, 0x28000
	s_mov_b32 s21, 0x30000
	s_mov_b32 s22, 0x38000
	s_mov_b32 s23, 0x40000
	s_mov_b32 s24, 0x48000
	s_mov_b32 s25, 0x50000
	s_mov_b32 s26, 0x58000
	s_mov_b32 s27, 0x60000
	s_mov_b32 s28, 0x68000
	s_mov_b32 s29, 0x70000
	s_mov_b32 s30, 0x78000
	s_mov_b32 s31, 0x80000
	s_mov_b32 s33, 0x88000
	s_mov_b32 s34, 0x90000
	s_mov_b32 s35, 0x98000
	s_mov_b32 s36, 0xa0000
	s_mov_b32 s37, 0xa8000
	s_mov_b32 s38, 0xb0000
	s_mov_b32 s39, 0xb8000
	s_mov_b32 s40, 0xc0000
	s_mov_b32 s41, 0xc8000
	s_mov_b32 s42, 0xd0000
	s_mov_b32 s43, 0xd8000
	s_mov_b32 s44, 0xe0000
	s_mov_b32 s45, 0xe8000
	s_mov_b32 s46, 0xf0000
	s_mov_b32 s47, 0xf8000
	s_mov_b32 s52, 0x9080
	v_lshlrev_b32_e32 v2, 2, v14
	v_add_u32_e32 v13, 0x400, v12
	v_add_u32_e32 v14, 0x800, v12
	v_add_u32_e32 v15, 0xc00, v12
	v_add_u32_e32 v16, 0x1000, v12
	v_add_u32_e32 v17, 0x1400, v12
	v_add_u32_e32 v18, 0x1800, v12
	v_add_u32_e32 v19, 0x1c00, v12
	v_mov_b32_e32 v20, 0x800
	s_mov_b32 s53, s8
	s_branch .LBB0_9

; __device__ __forceinline__ void rms_row_to_bf16(const float* xrow, const float* w, bf16* orow, int lane) {
;     const f32x4* xr = (const f32x4*)xrow + 2 * lane; f32x4 v[16];
; #pragma unroll
;     for (int j = 0; j < 8; ++j) { v[2 * j] = xr[128 * j]; v[2 * j + 1] = xr[128 * j + 1]; }
;     rms_regs_to_bf16(v, w, orow, lane);
; __device__ __forceinline__ void p0_prologue(const Frame& F, const Ptrs& P) {
;     const int gw = F.bid * NWAVES + F.wave, NGW = F.G * NWAVES;
;     convert_weights<0>(F, gw, NGW);
;     for (int m = gw; m < M; m += NGW) { const float* xr = (m < MP) ? P_x_prompt + (size_t)m * DM : P_x_sample + (size_t)(m - MP) * DM; rms_row_to_bf16(xr, P_mix_nw, P_XN + (size_t)m * DM, F.lane); }
.LBB0_13:
	s_cmp_eq_u32 s98, 2
	s_cbranch_scc1 .LBB0_20x
	s_cmpk_gt_i32 s8, 0x23ff
	s_cbranch_scc1 .LBB0_20
	v_mbcnt_lo_u32_b32 v1, -1, 0
	v_mov_b32_e32 v67, 0
	v_lshlrev_b32_e32 v66, 4, v189
	v_mbcnt_hi_u32_b32 v3, -1, v1
	v_lshl_add_u64 v[4:5], s[50:51], 0, v[66:67]
	s_mov_b64 s[4:5], 0x10400000
	v_and_b32_e32 v1, 64, v3
	v_lshl_add_u64 v[68:69], v[4:5], 0, s[4:5]
	v_add_u32_e32 v4, 64, v1
	v_xor_b32_e32 v1, 1, v3
	v_cmp_lt_i32_e32 vcc, v1, v4
	v_xor_b32_e32 v5, 2, v3
	s_load_dwordx2 s[4:5], s[0:1], 0x40
	v_cndmask_b32_e32 v1, v3, v1, vcc
	v_cmp_lt_i32_e32 vcc, v5, v4
	v_lshlrev_b32_e32 v66, 5, v189
	v_lshlrev_b32_e32 v2, 1, v189
	v_cndmask_b32_e32 v5, v3, v5, vcc
	v_lshlrev_b32_e32 v85, 2, v5
	v_xor_b32_e32 v5, 4, v3
	v_cmp_lt_i32_e32 vcc, v5, v4
	s_waitcnt lgkmcnt(0)
	v_lshl_add_u64 v[70:71], s[4:5], 0, v[66:67]
	s_mov_b64 s[14:15], 0x1000
	v_cndmask_b32_e32 v5, v3, v5, vcc
	v_lshlrev_b32_e32 v86, 2, v5
	v_xor_b32_e32 v5, 8, v3
	v_cmp_lt_i32_e32 vcc, v5, v4
	s_mov_b64 s[16:17], 0x1800
	s_mov_b64 s[18:19], 0x2000
	v_cndmask_b32_e32 v5, v3, v5, vcc
	v_lshlrev_b32_e32 v87, 2, v5
	v_xor_b32_e32 v5, 16, v3
	v_cmp_lt_i32_e32 vcc, v5, v4
	s_mov_b64 s[20:21], 0x2800
	s_mov_b64 s[22:23], 0x3000
	v_cndmask_b32_e32 v5, v3, v5, vcc
	v_lshlrev_b32_e32 v88, 2, v5
	v_xor_b32_e32 v5, 32, v3
	v_cmp_lt_i32_e32 vcc, v5, v4
	s_mov_b64 s[24:25], 0x3800
	s_ashr_i32 s9, s8, 31
	v_cndmask_b32_e32 v3, v3, v5, vcc
	s_ashr_i32 s11, s10, 31
	s_mov_b32 s13, 0
	v_lshlrev_b32_e32 v1, 2, v1
	v_lshlrev_b32_e32 v89, 2, v3
	v_lshl_add_u64 v[72:73], v[70:71], 0, s[14:15]
	v_lshl_add_u64 v[74:75], v[70:71], 0, s[16:17]
	v_lshl_add_u64 v[76:77], v[70:71], 0, s[18:19]
	v_lshl_add_u64 v[78:79], v[70:71], 0, s[20:21]
	v_lshl_add_u64 v[80:81], v[70:71], 0, s[22:23]
	v_lshl_add_u64 v[82:83], v[70:71], 0, s[24:25]
	s_lshl_b64 s[26:27], s[8:9], 14
	s_lshl_b64 s[28:29], s[10:11], 14
	v_lshlrev_b32_e32 v66, 4, v2
	s_movk_i32 s33, 0x1000
	s_movk_i32 s36, 0x2000
	s_movk_i32 s37, 0x3000
	v_mov_b32_e32 v90, 0x358637bd
	s_mov_b32 s38, 0xf800000
	v_mov_b32_e32 v91, 0x260
	s_branch .LBB0_16

; __device__ __forceinline__ void p0_prologue(const Frame& F, const Ptrs& P) {
;     const int gw = F.bid * NWAVES + F.wave, NGW = F.G * NWAVES;
;     convert_weights<0>(F, gw, NGW);
;     for (int m = gw; m < M; m += NGW) { const float* xr = (m < MP) ? P_x_prompt + (size_t)m * DM : P_x_sample + (size_t)(m - MP) * DM; rms_row_to_bf16(xr, P_mix_nw, P_XN + (size_t)m * DM, F.lane); }
; }
.LBB0_20:
	s_cmp_eq_u32 s98, 1
	s_cbranch_scc0 .LBB0_20x
	s_mov_b32 s98, 2
	s_branch .Lp0_conv_entry
